# co-resident stagger keyed on HW wave slot (HW_ID.WAVE_ID odd -> half k-step late entry to gemm_in / ffn_in); otherwise v111
# speedup vs baseline: 1.0044x; 1.0044x over previous
.LBB0_209:
	s_not_b32 s2, s5
	s_add_i32 s2, s8, s2
	s_add_i32 s2, s2, s17
	s_ashr_i32 s3, s2, 31
	s_abs_i32 s2, s2
	s_mul_hi_u32 s5, s2, s72
	s_mul_i32 s8, s5, s4
	s_sub_i32 s2, s2, s8
	s_xor_b32 s3, s3, s16
	s_add_i32 s8, s5, 1
	s_sub_i32 s9, s2, s4
	s_cmp_ge_u32 s2, s4
	s_cselect_b32 s5, s8, s5
	s_cselect_b32 s2, s9, s2
	s_add_i32 s8, s5, 1
	s_cmp_ge_u32 s2, s4
	s_cselect_b32 s2, s8, s5
	s_xor_b32 s2, s2, s3
	s_sub_i32 s2, s2, s3
	s_add_i32 s3, s15, s24
	s_not_b32 s4, s23
	s_add_i32 s4, s4, s3
	s_ashr_i32 s3, s4, 31
	s_abs_i32 s4, s4
	s_mul_i32 s1, s4, s1
	s_mul_hi_u32 s0, s4, s0
	s_add_i32 s0, s0, s1
	s_mul_i32 s1, s0, s12
	s_sub_i32 s1, s4, s1
	s_xor_b32 s3, s3, s13
	s_add_i32 s4, s0, 1
	s_sub_i32 s5, s1, s12
	s_cmp_ge_u32 s1, s12
	s_cselect_b32 s0, s4, s0
	s_cselect_b32 s1, s5, s1
	s_add_i32 s4, s0, 1
	s_cmp_ge_u32 s1, s12
	s_cselect_b32 s0, s4, s0
	s_xor_b32 s0, s0, s3
	s_sub_i32 s3, s0, s3
	s_cmp_lt_i32 s22, 0
	s_cselect_b64 s[8:9], -1, 0
	s_and_b64 s[0:1], s[8:9], exec
	s_cselect_b32 s26, s3, s2
	s_not_b32 s0, s14
	s_lshr_b32 s0, s0, 31
	s_add_i32 s26, s26, s0
	s_cmp_lt_i32 s26, 1
	s_cbranch_scc1 .LBB0_476
	s_lshr_b32 s27, s10, 3
	s_cmp_lt_i32 s14, 0
	s_mul_hi_u32 s0, s14, 0x3521cfb3
	s_cselect_b64 s[10:11], -1, 0
	s_sub_i32 s2, s14, s0
	s_lshr_b32 s2, s2, 1
	s_add_i32 s2, s2, s0
	s_lshr_b32 s0, s2, 5
	s_add_i32 s28, s0, 0x80
	s_mul_i32 s0, s0, 53
	v_and_b32_e32 v2, 15, v0
	s_sub_i32 s29, s14, s0
	v_ashrrev_i32_e32 v3, 1, v0
	s_movk_i32 s0, 0xffc0
	v_and_or_b32 v87, v3, s0, v2
	v_lshrrev_b32_e32 v2, 2, v0
	v_and_b32_e32 v2, 12, v2
	v_and_or_b32 v86, v0, 64, v2
	v_and_b32_e32 v0, 64, v0
	v_cmp_ne_u32_e64 s[40:41], 0, v0
	v_or_b32_e32 v0, 16, v86
	v_cmp_gt_u32_e64 s[44:45], 40, v0
	v_or_b32_e32 v0, 32, v86
	v_cmp_gt_u32_e64 s[4:5], 40, v0
	v_cvt_f32_u32_e32 v0, s25
	v_readlane_b32 s2, v249, 52
	s_load_dwordx2 s[12:13], s[6:7], 0x138
	s_load_dwordx2 s[14:15], s[6:7], 0xe0
	s_lshl_b32 s0, s2, 8
	v_rcp_iflag_f32_e32 v0, v0
	s_or_b32 s30, s0, 0xffffc000
	s_sub_i32 s0, 0, s25
	s_mov_b32 s18, s2
	v_mul_f32_e32 v0, 0x4f7ffffe, v0
	v_cvt_u32_f32_e32 v0, v0
	v_readlane_b32 s3, v249, 53
	s_mul_i32 s72, s2, 0xc00
	s_lshl_b32 s31, s2, 14
	v_readfirstlane_b32 s16, v0
	s_mul_i32 s0, s0, s16
	s_mul_hi_u32 s0, s16, s0
	s_lshl_b32 s2, s2, 6
	s_add_i32 s33, s16, s0
	s_mul_i32 s16, s18, 0xd40000
	s_mov_b32 s3, s73
	s_mul_hi_u32 s0, s18, 0xd40000
	s_waitcnt lgkmcnt(0)
	s_add_u32 s34, s14, s16
	s_mov_b32 s1, 0
	v_or_b32_e32 v104, 0xfffff180, v86
	v_cmp_gt_u32_e64 s[42:43], 40, v86
	s_addc_u32 s35, s15, s0
	s_lshl_b64 s[16:17], s[72:73], 2
	s_lshl_b64 s[18:19], s[2:3], 2
	v_lshlrev_b32_e32 v105, 2, v2
	s_mov_b32 s32, 0
	v_readlane_b32 s2, v249, 1
	s_nop 0
	s_cmpk_lg_u32 s2, 0x200
	s_cbranch_scc1 .LBB0_212
	s_getreg_b32 s2, hwreg(HW_REG_HW_ID, 0, 4)
	s_and_b32 s2, s2, 1
	s_cmp_eq_u32 s2, 0
	s_cbranch_scc1 .Lg2_nostag
	s_sleep 41

.LBB0_2352:
	v_and_b32_e32 v2, 15, v0
	v_ashrrev_i32_e32 v3, 1, v0
	s_movk_i32 s8, 0xffc0
	s_waitcnt vmcnt(2)
	v_and_or_b32 v74, v3, s8, v2
	v_lshrrev_b32_e32 v2, 1, v0
	v_lshrrev_b32_e32 v0, 2, v0
	s_and_b32 s17, s2, 7
	v_and_b32_e32 v0, 12, v0
	v_and_or_b32 v75, v2, 32, v0
	v_cvt_f32_ubyte0_e32 v0, s17
	v_rcp_iflag_f32_e32 v0, v0
	s_lshr_b32 s16, s2, 3
	s_cmp_lt_i32 s12, 0
	s_cselect_b64 s[2:3], -1, 0
	v_mul_f32_e32 v0, 0x4f7ffffe, v0
	v_cvt_u32_f32_e32 v0, v0
	s_sub_i32 s8, 0, s17
	s_load_dwordx2 s[4:5], s[0:1], 0x108
	s_load_dwordx2 s[6:7], s[0:1], 0x138
	v_readfirstlane_b32 s9, v0
	s_mul_i32 s8, s8, s9
	s_mul_hi_u32 s8, s9, s8
	s_add_i32 s18, s9, s8
	v_readlane_b32 s8, v249, 52
	v_readlane_b32 s9, v249, 53
	s_mov_b32 s10, s8
	s_mul_i32 s9, s10, 0xb00000
	s_mul_hi_u32 s8, s8, 0xb00000
	s_waitcnt lgkmcnt(0)
	s_add_u32 s19, s4, s9
	s_addc_u32 s20, s5, s8
	s_waitcnt vmcnt(0)
	s_mov_b32 s32, 0
	v_readlane_b32 s30, v249, 1
	s_nop 0
	s_cmpk_lg_u32 s30, 0x200
	s_cbranch_scc1 .LBB0_2354
	s_getreg_b32 s30, hwreg(HW_REG_HW_ID, 0, 4)
	s_and_b32 s30, s30, 1
	s_cmp_eq_u32 s30, 0
	s_cbranch_scc1 .Lf2_nostag
	s_sleep 41
